# P4 out-projection K-loop gets the same hand-scheduled loop as P1
# speedup vs baseline: 1.2454x; 1.0016x over previous
.LBB0_1786:
	s_and_b32 s0, s42, 56
	s_add_i32 s0, s41, s0
	s_bfe_u32 s26, s43, 0x30003
	s_add_i32 s16, s0, s26
	s_lshl_b64 s[0:1], s[16:17], 19
	s_waitcnt lgkmcnt(0)
	s_add_u32 s24, s2, s0
	s_addc_u32 s25, s3, s1
	s_lshl_b32 s0, s43, 3
	v_mov_b32_e32 v130, v132
	s_and_b32 s0, s0, 56
	s_or_b32 s0, s0, s41
	v_mov_b32_e32 v2, v130
	s_ashr_i32 s44, s43, 6
	s_barrier
	s_or_b32 s16, s0, s26
	v_lshlrev_b32_e32 v3, 4, v2
	s_waitcnt vmcnt(0)
	v_and_b32_e32 v4, 32, v2
	s_lshl_b32 s0, s44, 8
	v_bitop3_b32 v4, v3, v4, 48 bitop3:0x6c
	v_lshlrev_b32_e32 v5, 9, v2
	s_ashr_i32 s1, s0, 31
	v_and_or_b32 v4, v5, s33, v4
	v_bfe_i32 v5, v2, 6, 22
	v_bfe_u32 v2, v2, 27, 1
	v_ashrrev_i32_e32 v0, 6, v130
	s_lshl_b32 s28, s16, 19
	s_lshl_b64 s[26:27], s[0:1], 11
	v_add_u32_e32 v2, v5, v2
	s_add_u32 s28, s2, s28
	v_lshlrev_b32_e32 v131, 10, v0
	v_and_b32_e32 v6, 0x3fffffe, v2
	v_lshlrev_b32_e32 v2, 14, v2
	s_addc_u32 s29, s3, 0
	v_add_u32_e32 v134, 0x8000, v131
	v_sub_u32_e32 v5, v5, v6
	v_and_or_b32 v2, v2, s34, v4
	v_readfirstlane_b32 s1, v131
	s_add_u32 s26, s12, s26
	v_lshl_add_u32 v2, v5, 6, v2
	s_mov_b32 m0, s1
	v_readfirstlane_b32 s1, v134
	s_addc_u32 s27, s13, s27
	v_mov_b32_e32 v174, v2
	global_load_lds_dwordx4 v2, s[28:29]
	s_mov_b32 m0, s1
	v_add_u32_e32 v135, 0x2000, v131
	global_load_lds_dwordx4 v2, s[26:27]
	v_add_u32_e32 v2, 0x2000, v3
	v_ashrrev_i32_e32 v2, 10, v2
	v_lshrrev_b32_e32 v5, 31, v2
	v_add_u32_e32 v5, v2, v5
	v_and_b32_e32 v6, 0x3fffffe, v5
	v_lshlrev_b32_e32 v5, 14, v5
	v_sub_u32_e32 v2, v2, v6
	v_and_or_b32 v5, v5, s34, v4
	v_readfirstlane_b32 s1, v135
	v_add_u32_e32 v136, 0xa000, v131
	v_lshl_add_u32 v2, v2, 6, v5
	s_mov_b32 m0, s1
	v_readfirstlane_b32 s1, v136
	v_mov_b32_e32 v175, v2
	global_load_lds_dwordx4 v2, s[28:29]
	s_mov_b32 m0, s1
	v_add_u32_e32 v137, 0x4000, v131
	global_load_lds_dwordx4 v2, s[26:27]
	v_add_u32_e32 v2, 0x4000, v3
	v_ashrrev_i32_e32 v2, 10, v2
	v_lshrrev_b32_e32 v5, 31, v2
	v_add_u32_e32 v5, v2, v5
	v_and_b32_e32 v6, 0x3fffffe, v5
	v_lshlrev_b32_e32 v5, 14, v5
	v_sub_u32_e32 v2, v2, v6
	v_and_or_b32 v5, v5, s34, v4
	v_readfirstlane_b32 s1, v137
	v_add_u32_e32 v138, 0xc000, v131
	v_lshl_add_u32 v2, v2, 6, v5
	s_mov_b32 m0, s1
	v_readfirstlane_b32 s1, v138
	v_mov_b32_e32 v176, v2
	global_load_lds_dwordx4 v2, s[28:29]
	s_mov_b32 m0, s1
	v_add_u32_e32 v139, 0x6000, v131
	global_load_lds_dwordx4 v2, s[26:27]
	v_add_u32_e32 v2, 0x6000, v3
	v_ashrrev_i32_e32 v2, 10, v2
	v_lshrrev_b32_e32 v3, 31, v2
	v_add_u32_e32 v3, v2, v3
	v_and_b32_e32 v5, 0x3fffffe, v3
	v_lshlrev_b32_e32 v3, 14, v3
	v_sub_u32_e32 v2, v2, v5
	v_and_or_b32 v3, v3, s34, v4
	v_readfirstlane_b32 s1, v139
	v_add_u32_e32 v140, 0xe000, v131
	v_lshl_add_u32 v2, v2, 6, v3
	s_mov_b32 m0, s1
	v_readfirstlane_b32 s1, v140
	v_mov_b32_e32 v177, v2
	global_load_lds_dwordx4 v2, s[28:29]
	s_mov_b32 m0, s1
	v_and_b32_e32 v1, 15, v130
	global_load_lds_dwordx4 v2, s[26:27]
	v_readfirstlane_b32 s45, v131
	s_add_u32 s98, s24, 0x80
	s_addc_u32 s99, s25, 0
	s_add_u32 s100, s26, 0x80
	s_addc_u32 s101, s27, 0
	s_add_u32 m0, s45, 0x10400
	s_nop 0
	global_load_lds_dwordx4 v174, s[98:99]
	s_add_u32 m0, s45, 0x18400
	s_nop 0
	global_load_lds_dwordx4 v174, s[100:101]
	s_add_u32 m0, s45, 0x12400
	s_nop 0
	global_load_lds_dwordx4 v175, s[98:99]
	s_add_u32 m0, s45, 0x1a400
	s_nop 0
	global_load_lds_dwordx4 v175, s[100:101]
	s_add_u32 m0, s45, 0x14400
	s_nop 0
	global_load_lds_dwordx4 v176, s[98:99]
	s_add_u32 m0, s45, 0x1c400
	s_nop 0
	global_load_lds_dwordx4 v176, s[100:101]
	s_add_u32 m0, s45, 0x16400
	s_nop 0
	global_load_lds_dwordx4 v177, s[98:99]
	s_add_u32 m0, s45, 0x1e400
	s_nop 0
	global_load_lds_dwordx4 v177, s[100:101]
	s_add_u32 s98, s98, 0x80
	s_addc_u32 s99, s99, 0
	s_add_u32 s100, s100, 0x80
	s_addc_u32 s101, s101, 0
	v_and_b32_e32 v2, 48, v130
	v_lshlrev_b32_e32 v1, 6, v1
	v_lshlrev_b32_e32 v4, 2, v130
	v_or_b32_e32 v3, v1, v2
	v_and_b32_e32 v4, 32, v4
	v_lshlrev_b32_e32 v0, 13, v0
	v_bitop3_b32 v141, v3, s35, v4 bitop3:0xde
	v_and_b32_e32 v3, 0x6000, v0
	v_lshlrev_b32_e32 v0, 6, v130
	v_and_b32_e32 v142, 0xffffc000, v0
	v_and_b32_e32 v0, 0x3c0, v0
	s_waitcnt vmcnt(8)
	v_bitop3_b32 v5, v0, v4, v2 bitop3:0x36
	v_or_b32_e32 v0, v0, v2
	v_bitop3_b32 v1, v1, v4, v2 bitop3:0x36
	v_or_b32_e32 v143, 0x800, v142
	v_or_b32_e32 v6, 0x1000, v142
	v_or_b32_e32 v7, 0x1800, v142
	v_or_b32_e32 v8, 0x2000, v142
	v_or_b32_e32 v9, 0x2800, v142
	v_or_b32_e32 v10, 0x3000, v142
	v_or_b32_e32 v2, 0x3800, v142
	v_bitop3_b32 v144, v0, s35, v4 bitop3:0xde
	v_mov_b32_e32 v0, 0
	s_mov_b32 s1, 0
	s_mov_b64 s[28:29], 0
	v_add_u32_e32 v145, 0x10400, v131
	v_add_u32_e32 v146, 0x18400, v131
	v_add_u32_e32 v147, 0x12400, v131
	v_add_u32_e32 v150, 0x1a400, v131
	v_add_u32_e32 v151, 0x14400, v131
	v_add_u32_e32 v152, 0x1c400, v131
	v_add_u32_e32 v153, 0x16400, v131
	v_add_u32_e32 v154, 0x1e400, v131
	v_add_u32_e32 v155, v1, v3
	v_add_u32_e32 v156, v1, v142
	v_add_u32_e32 v157, v5, v143
	v_add_u32_e32 v158, v5, v6
	v_add_u32_e32 v159, v5, v7
	v_add_u32_e32 v160, v5, v8
	v_add_u32_e32 v161, v5, v9
	v_add_u32_e32 v162, v5, v10
	v_add_u32_e32 v163, v5, v2
	v_add_u32_e32 v164, v141, v3
	v_add_u32_e32 v165, v144, v6
	v_add_u32_e32 v166, v144, v7
	v_add_u32_e32 v167, v144, v8
	v_add_u32_e32 v168, v144, v9
	v_add_u32_e32 v169, v144, v10
	v_add_u32_e32 v170, v144, v2
	v_mov_b32_e32 v1, v0
	v_mov_b32_e32 v2, v0
	v_mov_b32_e32 v3, v0
	v_mov_b32_e32 v4, v0
	v_mov_b32_e32 v5, v0
	v_mov_b32_e32 v6, v0
	v_mov_b32_e32 v7, v0
	v_mov_b32_e32 v8, v0
	v_mov_b32_e32 v9, v0
	v_mov_b32_e32 v10, v0
	v_mov_b32_e32 v11, v0
	v_mov_b32_e32 v12, v0
	v_mov_b32_e32 v13, v0
	v_mov_b32_e32 v14, v0
	v_mov_b32_e32 v15, v0
	v_mov_b32_e32 v16, v0
	v_mov_b32_e32 v17, v0
	v_mov_b32_e32 v18, v0
	v_mov_b32_e32 v19, v0
	v_mov_b32_e32 v20, v0
	v_mov_b32_e32 v21, v0
	v_mov_b32_e32 v22, v0
	v_mov_b32_e32 v23, v0
	v_mov_b32_e32 v24, v0
	v_mov_b32_e32 v25, v0
	v_mov_b32_e32 v26, v0
	v_mov_b32_e32 v27, v0
	v_mov_b32_e32 v28, v0
	v_mov_b32_e32 v29, v0
	v_mov_b32_e32 v30, v0
	v_mov_b32_e32 v31, v0
	v_mov_b32_e32 v32, v0
	v_mov_b32_e32 v33, v0
	v_mov_b32_e32 v34, v0
	v_mov_b32_e32 v35, v0
	v_mov_b32_e32 v36, v0
	v_mov_b32_e32 v37, v0
	v_mov_b32_e32 v38, v0
	v_mov_b32_e32 v39, v0
	v_mov_b32_e32 v40, v0
	v_mov_b32_e32 v41, v0
	v_mov_b32_e32 v42, v0
	v_mov_b32_e32 v43, v0
	v_mov_b32_e32 v44, v0
	v_mov_b32_e32 v45, v0
	v_mov_b32_e32 v46, v0
	v_mov_b32_e32 v47, v0
	v_mov_b32_e32 v48, v0
	v_mov_b32_e32 v49, v0
	v_mov_b32_e32 v50, v0
	v_mov_b32_e32 v51, v0
	v_mov_b32_e32 v52, v0
	v_mov_b32_e32 v53, v0
	v_mov_b32_e32 v54, v0
	v_mov_b32_e32 v55, v0
	v_mov_b32_e32 v56, v0
	v_mov_b32_e32 v57, v0
	v_mov_b32_e32 v58, v0
	v_mov_b32_e32 v59, v0
	v_mov_b32_e32 v60, v0
	v_mov_b32_e32 v61, v0
	v_mov_b32_e32 v62, v0
	v_mov_b32_e32 v63, v0
	v_mov_b32_e32 v64, v0
	v_mov_b32_e32 v65, v0
	v_mov_b32_e32 v66, v0
	v_mov_b32_e32 v67, v0
	v_mov_b32_e32 v68, v0
	v_mov_b32_e32 v69, v0
	v_mov_b32_e32 v70, v0
	v_mov_b32_e32 v71, v0
	v_mov_b32_e32 v72, v0
	v_mov_b32_e32 v73, v0
	v_mov_b32_e32 v74, v0
	v_mov_b32_e32 v75, v0
	v_mov_b32_e32 v76, v0
	v_mov_b32_e32 v77, v0
	v_mov_b32_e32 v78, v0
	v_mov_b32_e32 v79, v0
	v_mov_b32_e32 v80, v0
	v_mov_b32_e32 v81, v0
	v_mov_b32_e32 v82, v0
	v_mov_b32_e32 v83, v0
	v_mov_b32_e32 v84, v0
	v_mov_b32_e32 v85, v0
	v_mov_b32_e32 v86, v0
	v_mov_b32_e32 v87, v0
	v_mov_b32_e32 v88, v0
	v_mov_b32_e32 v89, v0
	v_mov_b32_e32 v90, v0
	v_mov_b32_e32 v91, v0
	v_mov_b32_e32 v92, v0
	v_mov_b32_e32 v93, v0
	v_mov_b32_e32 v94, v0
	v_mov_b32_e32 v95, v0
	v_mov_b32_e32 v96, v0
	v_mov_b32_e32 v97, v0
	v_mov_b32_e32 v98, v0
	v_mov_b32_e32 v99, v0
	v_mov_b32_e32 v100, v0
	v_mov_b32_e32 v101, v0
	v_mov_b32_e32 v102, v0
	v_mov_b32_e32 v103, v0
	v_mov_b32_e32 v104, v0
	v_mov_b32_e32 v105, v0
	v_mov_b32_e32 v106, v0
	v_mov_b32_e32 v107, v0
	v_mov_b32_e32 v108, v0
	v_mov_b32_e32 v109, v0
	v_mov_b32_e32 v110, v0
	v_mov_b32_e32 v111, v0
	v_mov_b32_e32 v112, v0
	v_mov_b32_e32 v113, v0
	v_mov_b32_e32 v114, v0
	v_mov_b32_e32 v115, v0
	v_mov_b32_e32 v116, v0
	v_mov_b32_e32 v117, v0
	v_mov_b32_e32 v118, v0
	v_mov_b32_e32 v119, v0
	v_mov_b32_e32 v120, v0
	v_mov_b32_e32 v121, v0
	v_mov_b32_e32 v122, v0
	v_mov_b32_e32 v123, v0
	v_mov_b32_e32 v124, v0
	v_mov_b32_e32 v125, v0
	v_mov_b32_e32 v126, v0
	v_mov_b32_e32 v127, v0
	v_add_u32_e32 v172, v141, v142
	v_add_u32_e32 v173, v144, v143
	s_waitcnt vmcnt(8) lgkmcnt(0)
	s_barrier
	ds_read_b128 v[178:181], v155 offset:32768
	ds_read_b128 v[182:185], v155 offset:34816
	ds_read_b128 v[186:189], v155 offset:36864
	ds_read_b128 v[190:193], v155 offset:38912
	ds_read_b128 v[210:213], v156
	ds_read_b128 v[214:217], v157
	ds_read_b128 v[218:221], v158
	s_branch .LBB0_1788
.LBB0_1788:
	ds_read_b128 v[222:225], v159
	ds_read_b128 v[226:229], v160
	ds_read_b128 v[230:233], v161
	s_waitcnt lgkmcnt(5)
	v_mfma_f32_16x16x32_bf16 v[124:127], v[210:213], v[178:181], v[124:127]
	v_mfma_f32_16x16x32_bf16 v[120:123], v[210:213], v[182:185], v[120:123]
	v_mfma_f32_16x16x32_bf16 v[116:119], v[210:213], v[186:189], v[116:119]
	v_mfma_f32_16x16x32_bf16 v[112:115], v[210:213], v[190:193], v[112:115]
	ds_read_b128 v[234:237], v162
	s_waitcnt lgkmcnt(5)
	v_mfma_f32_16x16x32_bf16 v[108:111], v[214:217], v[178:181], v[108:111]
	v_mfma_f32_16x16x32_bf16 v[104:107], v[214:217], v[182:185], v[104:107]
	v_mfma_f32_16x16x32_bf16 v[100:103], v[214:217], v[186:189], v[100:103]
	v_mfma_f32_16x16x32_bf16 v[96:99], v[214:217], v[190:193], v[96:99]
	ds_read_b128 v[238:241], v163
	ds_read_b128 v[194:197], v155 offset:33792
	s_waitcnt lgkmcnt(6)
	v_mfma_f32_16x16x32_bf16 v[92:95], v[218:221], v[178:181], v[92:95]
	v_mfma_f32_16x16x32_bf16 v[88:91], v[218:221], v[182:185], v[88:91]
	v_mfma_f32_16x16x32_bf16 v[84:87], v[218:221], v[186:189], v[84:87]
	v_mfma_f32_16x16x32_bf16 v[80:83], v[218:221], v[190:193], v[80:83]
	ds_read_b128 v[210:213], v156 offset:1024
	ds_read_b128 v[198:201], v155 offset:35840
	s_waitcnt lgkmcnt(7)
	v_mfma_f32_16x16x32_bf16 v[76:79], v[222:225], v[178:181], v[76:79]
	v_mfma_f32_16x16x32_bf16 v[72:75], v[222:225], v[182:185], v[72:75]
	v_mfma_f32_16x16x32_bf16 v[68:71], v[222:225], v[186:189], v[68:71]
	v_mfma_f32_16x16x32_bf16 v[64:67], v[222:225], v[190:193], v[64:67]
	ds_read_b128 v[214:217], v157 offset:1024
	ds_read_b128 v[202:205], v155 offset:37888
	s_waitcnt lgkmcnt(8)
	v_mfma_f32_16x16x32_bf16 v[60:63], v[226:229], v[178:181], v[60:63]
	v_mfma_f32_16x16x32_bf16 v[56:59], v[226:229], v[182:185], v[56:59]
	v_mfma_f32_16x16x32_bf16 v[52:55], v[226:229], v[186:189], v[52:55]
	v_mfma_f32_16x16x32_bf16 v[48:51], v[226:229], v[190:193], v[48:51]
	ds_read_b128 v[218:221], v158 offset:1024
	ds_read_b128 v[206:209], v155 offset:39936
	s_waitcnt lgkmcnt(9)
	v_mfma_f32_16x16x32_bf16 v[44:47], v[230:233], v[178:181], v[44:47]
	v_mfma_f32_16x16x32_bf16 v[40:43], v[230:233], v[182:185], v[40:43]
	v_mfma_f32_16x16x32_bf16 v[36:39], v[230:233], v[186:189], v[36:39]
	v_mfma_f32_16x16x32_bf16 v[32:35], v[230:233], v[190:193], v[32:35]
	ds_read_b128 v[222:225], v159 offset:1024
	s_waitcnt lgkmcnt(9)
	v_mfma_f32_16x16x32_bf16 v[28:31], v[234:237], v[178:181], v[28:31]
	v_mfma_f32_16x16x32_bf16 v[24:27], v[234:237], v[182:185], v[24:27]
	v_mfma_f32_16x16x32_bf16 v[20:23], v[234:237], v[186:189], v[20:23]
	v_mfma_f32_16x16x32_bf16 v[16:19], v[234:237], v[190:193], v[16:19]
	ds_read_b128 v[226:229], v160 offset:1024
	s_waitcnt lgkmcnt(9)
	v_mfma_f32_16x16x32_bf16 v[12:15], v[238:241], v[178:181], v[12:15]
	v_mfma_f32_16x16x32_bf16 v[8:11], v[238:241], v[182:185], v[8:11]
	v_mfma_f32_16x16x32_bf16 v[4:7], v[238:241], v[186:189], v[4:7]
	v_mfma_f32_16x16x32_bf16 v[0:3], v[238:241], v[190:193], v[0:3]
	ds_read_b128 v[230:233], v161 offset:1024
	s_waitcnt lgkmcnt(3)
	v_mfma_f32_16x16x32_bf16 v[124:127], v[210:213], v[194:197], v[124:127]
	v_mfma_f32_16x16x32_bf16 v[120:123], v[210:213], v[198:201], v[120:123]
	v_mfma_f32_16x16x32_bf16 v[116:119], v[210:213], v[202:205], v[116:119]
	v_mfma_f32_16x16x32_bf16 v[112:115], v[210:213], v[206:209], v[112:115]
	ds_read_b128 v[234:237], v162 offset:1024
	v_mfma_f32_16x16x32_bf16 v[108:111], v[214:217], v[194:197], v[108:111]
	v_mfma_f32_16x16x32_bf16 v[104:107], v[214:217], v[198:201], v[104:107]
	v_mfma_f32_16x16x32_bf16 v[100:103], v[214:217], v[202:205], v[100:103]
	v_mfma_f32_16x16x32_bf16 v[96:99], v[214:217], v[206:209], v[96:99]
	ds_read_b128 v[238:241], v163 offset:1024
	v_mfma_f32_16x16x32_bf16 v[92:95], v[218:221], v[194:197], v[92:95]
	v_mfma_f32_16x16x32_bf16 v[88:91], v[218:221], v[198:201], v[88:91]
	v_mfma_f32_16x16x32_bf16 v[84:87], v[218:221], v[202:205], v[84:87]
	v_mfma_f32_16x16x32_bf16 v[80:83], v[218:221], v[206:209], v[80:83]
	s_waitcnt lgkmcnt(4)
	v_mfma_f32_16x16x32_bf16 v[76:79], v[222:225], v[194:197], v[76:79]
	v_mfma_f32_16x16x32_bf16 v[72:75], v[222:225], v[198:201], v[72:75]
	v_mfma_f32_16x16x32_bf16 v[68:71], v[222:225], v[202:205], v[68:71]
	v_mfma_f32_16x16x32_bf16 v[64:67], v[222:225], v[206:209], v[64:67]
	s_waitcnt lgkmcnt(0)
	s_waitcnt vmcnt(0)
	s_barrier
	ds_read_b128 v[178:181], v164 offset:32768
	ds_read_b128 v[182:185], v164 offset:34816
	ds_read_b128 v[186:189], v164 offset:36864
	ds_read_b128 v[190:193], v164 offset:38912
	ds_read_b128 v[210:213], v172
	ds_read_b128 v[214:217], v173
	ds_read_b128 v[218:221], v165
	s_cmp_gt_u32 s1, 13
	s_cbranch_scc1 .Lg4_nostage0
	s_add_u32 m0, s45, 0x0
	v_mfma_f32_16x16x32_bf16 v[60:63], v[226:229], v[194:197], v[60:63]
	global_load_lds_dwordx4 v174, s[98:99]
	s_add_u32 m0, s45, 0x8000
	v_mfma_f32_16x16x32_bf16 v[56:59], v[226:229], v[198:201], v[56:59]
	global_load_lds_dwordx4 v174, s[100:101]
	v_mfma_f32_16x16x32_bf16 v[52:55], v[226:229], v[202:205], v[52:55]
	v_mfma_f32_16x16x32_bf16 v[48:51], v[226:229], v[206:209], v[48:51]
	s_add_u32 m0, s45, 0x2000
	v_mfma_f32_16x16x32_bf16 v[44:47], v[230:233], v[194:197], v[44:47]
	global_load_lds_dwordx4 v175, s[98:99]
	s_add_u32 m0, s45, 0xa000
	v_mfma_f32_16x16x32_bf16 v[40:43], v[230:233], v[198:201], v[40:43]
	global_load_lds_dwordx4 v175, s[100:101]
	v_mfma_f32_16x16x32_bf16 v[36:39], v[230:233], v[202:205], v[36:39]
	v_mfma_f32_16x16x32_bf16 v[32:35], v[230:233], v[206:209], v[32:35]
	s_add_u32 m0, s45, 0x4000
	v_mfma_f32_16x16x32_bf16 v[28:31], v[234:237], v[194:197], v[28:31]
	global_load_lds_dwordx4 v176, s[98:99]
	s_add_u32 m0, s45, 0xc000
	v_mfma_f32_16x16x32_bf16 v[24:27], v[234:237], v[198:201], v[24:27]
	global_load_lds_dwordx4 v176, s[100:101]
	v_mfma_f32_16x16x32_bf16 v[20:23], v[234:237], v[202:205], v[20:23]
	v_mfma_f32_16x16x32_bf16 v[16:19], v[234:237], v[206:209], v[16:19]
	s_add_u32 m0, s45, 0x6000
	v_mfma_f32_16x16x32_bf16 v[12:15], v[238:241], v[194:197], v[12:15]
	global_load_lds_dwordx4 v177, s[98:99]
	s_add_u32 m0, s45, 0xe000
	v_mfma_f32_16x16x32_bf16 v[8:11], v[238:241], v[198:201], v[8:11]
	global_load_lds_dwordx4 v177, s[100:101]
	v_mfma_f32_16x16x32_bf16 v[4:7], v[238:241], v[202:205], v[4:7]
	v_mfma_f32_16x16x32_bf16 v[0:3], v[238:241], v[206:209], v[0:3]
	s_add_u32 s98, s98, 0x80
	s_addc_u32 s99, s99, 0
	s_add_u32 s100, s100, 0x80
	s_addc_u32 s101, s101, 0
	s_branch .Lg4_half1
.Lg4_nostage0:
	v_mfma_f32_16x16x32_bf16 v[60:63], v[226:229], v[194:197], v[60:63]
	v_mfma_f32_16x16x32_bf16 v[56:59], v[226:229], v[198:201], v[56:59]
	v_mfma_f32_16x16x32_bf16 v[52:55], v[226:229], v[202:205], v[52:55]
	v_mfma_f32_16x16x32_bf16 v[48:51], v[226:229], v[206:209], v[48:51]
	v_mfma_f32_16x16x32_bf16 v[44:47], v[230:233], v[194:197], v[44:47]
	v_mfma_f32_16x16x32_bf16 v[40:43], v[230:233], v[198:201], v[40:43]
	v_mfma_f32_16x16x32_bf16 v[36:39], v[230:233], v[202:205], v[36:39]
	v_mfma_f32_16x16x32_bf16 v[32:35], v[230:233], v[206:209], v[32:35]
	v_mfma_f32_16x16x32_bf16 v[28:31], v[234:237], v[194:197], v[28:31]
	v_mfma_f32_16x16x32_bf16 v[24:27], v[234:237], v[198:201], v[24:27]
	v_mfma_f32_16x16x32_bf16 v[20:23], v[234:237], v[202:205], v[20:23]
	v_mfma_f32_16x16x32_bf16 v[16:19], v[234:237], v[206:209], v[16:19]
	v_mfma_f32_16x16x32_bf16 v[12:15], v[238:241], v[194:197], v[12:15]
	v_mfma_f32_16x16x32_bf16 v[8:11], v[238:241], v[198:201], v[8:11]
	v_mfma_f32_16x16x32_bf16 v[4:7], v[238:241], v[202:205], v[4:7]
	v_mfma_f32_16x16x32_bf16 v[0:3], v[238:241], v[206:209], v[0:3]
.Lg4_half1:
	ds_read_b128 v[222:225], v166
	ds_read_b128 v[226:229], v167
	ds_read_b128 v[230:233], v168
	s_waitcnt lgkmcnt(5)
	v_mfma_f32_16x16x32_bf16 v[124:127], v[210:213], v[178:181], v[124:127]
	v_mfma_f32_16x16x32_bf16 v[120:123], v[210:213], v[182:185], v[120:123]
	v_mfma_f32_16x16x32_bf16 v[116:119], v[210:213], v[186:189], v[116:119]
	v_mfma_f32_16x16x32_bf16 v[112:115], v[210:213], v[190:193], v[112:115]
	ds_read_b128 v[234:237], v169
	s_waitcnt lgkmcnt(5)
	v_mfma_f32_16x16x32_bf16 v[108:111], v[214:217], v[178:181], v[108:111]
	v_mfma_f32_16x16x32_bf16 v[104:107], v[214:217], v[182:185], v[104:107]
	v_mfma_f32_16x16x32_bf16 v[100:103], v[214:217], v[186:189], v[100:103]
	v_mfma_f32_16x16x32_bf16 v[96:99], v[214:217], v[190:193], v[96:99]
	ds_read_b128 v[238:241], v170
	ds_read_b128 v[194:197], v164 offset:33792
	s_waitcnt lgkmcnt(6)
	v_mfma_f32_16x16x32_bf16 v[92:95], v[218:221], v[178:181], v[92:95]
	v_mfma_f32_16x16x32_bf16 v[88:91], v[218:221], v[182:185], v[88:91]
	v_mfma_f32_16x16x32_bf16 v[84:87], v[218:221], v[186:189], v[84:87]
	v_mfma_f32_16x16x32_bf16 v[80:83], v[218:221], v[190:193], v[80:83]
	ds_read_b128 v[210:213], v172 offset:1024
	ds_read_b128 v[198:201], v164 offset:35840
	s_waitcnt lgkmcnt(7)
	v_mfma_f32_16x16x32_bf16 v[76:79], v[222:225], v[178:181], v[76:79]
	v_mfma_f32_16x16x32_bf16 v[72:75], v[222:225], v[182:185], v[72:75]
	v_mfma_f32_16x16x32_bf16 v[68:71], v[222:225], v[186:189], v[68:71]
	v_mfma_f32_16x16x32_bf16 v[64:67], v[222:225], v[190:193], v[64:67]
	ds_read_b128 v[214:217], v173 offset:1024
	ds_read_b128 v[202:205], v164 offset:37888
	s_waitcnt lgkmcnt(8)
	v_mfma_f32_16x16x32_bf16 v[60:63], v[226:229], v[178:181], v[60:63]
	v_mfma_f32_16x16x32_bf16 v[56:59], v[226:229], v[182:185], v[56:59]
	v_mfma_f32_16x16x32_bf16 v[52:55], v[226:229], v[186:189], v[52:55]
	v_mfma_f32_16x16x32_bf16 v[48:51], v[226:229], v[190:193], v[48:51]
	ds_read_b128 v[218:221], v165 offset:1024
	ds_read_b128 v[206:209], v164 offset:39936
	s_waitcnt lgkmcnt(9)
	v_mfma_f32_16x16x32_bf16 v[44:47], v[230:233], v[178:181], v[44:47]
	v_mfma_f32_16x16x32_bf16 v[40:43], v[230:233], v[182:185], v[40:43]
	v_mfma_f32_16x16x32_bf16 v[36:39], v[230:233], v[186:189], v[36:39]
	v_mfma_f32_16x16x32_bf16 v[32:35], v[230:233], v[190:193], v[32:35]
	ds_read_b128 v[222:225], v166 offset:1024
	s_waitcnt lgkmcnt(9)
	v_mfma_f32_16x16x32_bf16 v[28:31], v[234:237], v[178:181], v[28:31]
	v_mfma_f32_16x16x32_bf16 v[24:27], v[234:237], v[182:185], v[24:27]
	v_mfma_f32_16x16x32_bf16 v[20:23], v[234:237], v[186:189], v[20:23]
	v_mfma_f32_16x16x32_bf16 v[16:19], v[234:237], v[190:193], v[16:19]
	ds_read_b128 v[226:229], v167 offset:1024
	s_waitcnt lgkmcnt(9)
	v_mfma_f32_16x16x32_bf16 v[12:15], v[238:241], v[178:181], v[12:15]
	v_mfma_f32_16x16x32_bf16 v[8:11], v[238:241], v[182:185], v[8:11]
	v_mfma_f32_16x16x32_bf16 v[4:7], v[238:241], v[186:189], v[4:7]
	v_mfma_f32_16x16x32_bf16 v[0:3], v[238:241], v[190:193], v[0:3]
	ds_read_b128 v[230:233], v168 offset:1024
	s_waitcnt lgkmcnt(3)
	v_mfma_f32_16x16x32_bf16 v[124:127], v[210:213], v[194:197], v[124:127]
	v_mfma_f32_16x16x32_bf16 v[120:123], v[210:213], v[198:201], v[120:123]
	v_mfma_f32_16x16x32_bf16 v[116:119], v[210:213], v[202:205], v[116:119]
	v_mfma_f32_16x16x32_bf16 v[112:115], v[210:213], v[206:209], v[112:115]
	ds_read_b128 v[234:237], v169 offset:1024
	v_mfma_f32_16x16x32_bf16 v[108:111], v[214:217], v[194:197], v[108:111]
	v_mfma_f32_16x16x32_bf16 v[104:107], v[214:217], v[198:201], v[104:107]
	v_mfma_f32_16x16x32_bf16 v[100:103], v[214:217], v[202:205], v[100:103]
	v_mfma_f32_16x16x32_bf16 v[96:99], v[214:217], v[206:209], v[96:99]
	ds_read_b128 v[238:241], v170 offset:1024
	v_mfma_f32_16x16x32_bf16 v[92:95], v[218:221], v[194:197], v[92:95]
	v_mfma_f32_16x16x32_bf16 v[88:91], v[218:221], v[198:201], v[88:91]
	v_mfma_f32_16x16x32_bf16 v[84:87], v[218:221], v[202:205], v[84:87]
	v_mfma_f32_16x16x32_bf16 v[80:83], v[218:221], v[206:209], v[80:83]
	s_waitcnt lgkmcnt(4)
	v_mfma_f32_16x16x32_bf16 v[76:79], v[222:225], v[194:197], v[76:79]
	v_mfma_f32_16x16x32_bf16 v[72:75], v[222:225], v[198:201], v[72:75]
	v_mfma_f32_16x16x32_bf16 v[68:71], v[222:225], v[202:205], v[68:71]
	v_mfma_f32_16x16x32_bf16 v[64:67], v[222:225], v[206:209], v[64:67]
	s_waitcnt lgkmcnt(0)
	s_waitcnt vmcnt(0)
	s_barrier
	s_cmp_gt_u32 s1, 13
	s_cbranch_scc1 .Lg4_last
	ds_read_b128 v[178:181], v155 offset:32768
	ds_read_b128 v[182:185], v155 offset:34816
	ds_read_b128 v[186:189], v155 offset:36864
	ds_read_b128 v[190:193], v155 offset:38912
	ds_read_b128 v[210:213], v156
	ds_read_b128 v[214:217], v157
	ds_read_b128 v[218:221], v158
	s_add_u32 m0, s45, 0x10400
	v_mfma_f32_16x16x32_bf16 v[60:63], v[226:229], v[194:197], v[60:63]
	global_load_lds_dwordx4 v174, s[98:99]
	s_add_u32 m0, s45, 0x18400
	v_mfma_f32_16x16x32_bf16 v[56:59], v[226:229], v[198:201], v[56:59]
	global_load_lds_dwordx4 v174, s[100:101]
	v_mfma_f32_16x16x32_bf16 v[52:55], v[226:229], v[202:205], v[52:55]
	v_mfma_f32_16x16x32_bf16 v[48:51], v[226:229], v[206:209], v[48:51]
	s_add_u32 m0, s45, 0x12400
	v_mfma_f32_16x16x32_bf16 v[44:47], v[230:233], v[194:197], v[44:47]
	global_load_lds_dwordx4 v175, s[98:99]
	s_add_u32 m0, s45, 0x1a400
	v_mfma_f32_16x16x32_bf16 v[40:43], v[230:233], v[198:201], v[40:43]
	global_load_lds_dwordx4 v175, s[100:101]
	v_mfma_f32_16x16x32_bf16 v[36:39], v[230:233], v[202:205], v[36:39]
	v_mfma_f32_16x16x32_bf16 v[32:35], v[230:233], v[206:209], v[32:35]
	s_add_u32 m0, s45, 0x14400
	v_mfma_f32_16x16x32_bf16 v[28:31], v[234:237], v[194:197], v[28:31]
	global_load_lds_dwordx4 v176, s[98:99]
	s_add_u32 m0, s45, 0x1c400
	v_mfma_f32_16x16x32_bf16 v[24:27], v[234:237], v[198:201], v[24:27]
	global_load_lds_dwordx4 v176, s[100:101]
	v_mfma_f32_16x16x32_bf16 v[20:23], v[234:237], v[202:205], v[20:23]
	v_mfma_f32_16x16x32_bf16 v[16:19], v[234:237], v[206:209], v[16:19]
	s_add_u32 m0, s45, 0x16400
	v_mfma_f32_16x16x32_bf16 v[12:15], v[238:241], v[194:197], v[12:15]
	global_load_lds_dwordx4 v177, s[98:99]
	s_add_u32 m0, s45, 0x1e400
	v_mfma_f32_16x16x32_bf16 v[8:11], v[238:241], v[198:201], v[8:11]
	global_load_lds_dwordx4 v177, s[100:101]
	v_mfma_f32_16x16x32_bf16 v[4:7], v[238:241], v[202:205], v[4:7]
	v_mfma_f32_16x16x32_bf16 v[0:3], v[238:241], v[206:209], v[0:3]
	s_add_u32 s98, s98, 0x80
	s_addc_u32 s99, s99, 0
	s_add_u32 s100, s100, 0x80
	s_addc_u32 s101, s101, 0
	s_add_i32 s1, s1, 2
	s_branch .LBB0_1788
.Lg4_last:
	v_mfma_f32_16x16x32_bf16 v[60:63], v[226:229], v[194:197], v[60:63]
	v_mfma_f32_16x16x32_bf16 v[56:59], v[226:229], v[198:201], v[56:59]
	v_mfma_f32_16x16x32_bf16 v[52:55], v[226:229], v[202:205], v[52:55]
	v_mfma_f32_16x16x32_bf16 v[48:51], v[226:229], v[206:209], v[48:51]
	v_mfma_f32_16x16x32_bf16 v[44:47], v[230:233], v[194:197], v[44:47]
	v_mfma_f32_16x16x32_bf16 v[40:43], v[230:233], v[198:201], v[40:43]
	v_mfma_f32_16x16x32_bf16 v[36:39], v[230:233], v[202:205], v[36:39]
	v_mfma_f32_16x16x32_bf16 v[32:35], v[230:233], v[206:209], v[32:35]
	v_mfma_f32_16x16x32_bf16 v[28:31], v[234:237], v[194:197], v[28:31]
	v_mfma_f32_16x16x32_bf16 v[24:27], v[234:237], v[198:201], v[24:27]
	v_mfma_f32_16x16x32_bf16 v[20:23], v[234:237], v[202:205], v[20:23]
	v_mfma_f32_16x16x32_bf16 v[16:19], v[234:237], v[206:209], v[16:19]
	v_mfma_f32_16x16x32_bf16 v[12:15], v[238:241], v[194:197], v[12:15]
	v_mfma_f32_16x16x32_bf16 v[8:11], v[238:241], v[198:201], v[8:11]
	v_mfma_f32_16x16x32_bf16 v[4:7], v[238:241], v[202:205], v[4:7]
	v_mfma_f32_16x16x32_bf16 v[0:3], v[238:241], v[206:209], v[0:3]
	s_nop 15
	s_nop 15
